# nsa_hidreduce accumulation loop: the 8 serialized load pairs (each with vmcnt(0)) issued together with counted waits, same addition order
# baseline (speedup 1.0000x reference)
; __device__ __forceinline__ unsigned pk2(float lo, float hi) { return f2bf(lo) | (f2bf(hi) << 16); }
; __device__ __forceinline__ float gelu_tanh(float x) { return x * __builtin_amdgcn_rcpf(1.f + __builtin_amdgcn_exp2f(x * __builtin_fmaf(-1.029432396e-01f, x * x, -2.302208198e+00f))); }
;     __device__ __forceinline__ const char* pb(const Unit& u) const { return (const char*)(Bt + (size_t)u.pn * b_tile_stride); }
; __device__ __forceinline__ void nsa_hidreduce(const Ctx& c, const float* HIDP, const float* pb, bf16* HID) {
;     for (int it = c.vcu * 512 + c.tid; it < 8192 * 32; it += c.G * 512) {
;         const int r = it >> 5, h0 = (it & 31) * 8, ten = r >> 12; const float* hrow = HIDP + (size_t)r * 2048 + h0;
;         f32x4 a0 = *(const f32x4*)(pb + ten * 256 + h0), a1 = *(const f32x4*)(pb + ten * 256 + h0 + 4);
; #pragma unroll
;         for (int sp = 0; sp < 8; ++sp) { a0 += *(const f32x4*)(hrow + sp * 256); a1 += *(const f32x4*)(hrow + sp * 256 + 4); }
;         v4u o; o.x = pk2(gelu_tanh(a0.x), gelu_tanh(a0.y)); o.y = pk2(gelu_tanh(a0.z), gelu_tanh(a0.w)); o.z = pk2(gelu_tanh(a1.x), gelu_tanh(a1.y)); o.w = pk2(gelu_tanh(a1.z), gelu_tanh(a1.w));
;         *(v4u*)(HID + (size_t)r * 256 + h0) = o;
;     }
.LBB0_2023:
	v_ashrrev_i32_e32 v26, 5, v8
	v_ashrrev_i32_e32 v27, 31, v26
	v_and_b32_e32 v9, 0xf8, v6
	v_lshlrev_b64 v[10:11], 13, v[26:27]
	v_lshl_add_u64 v[10:11], s[78:79], 0, v[10:11]
	v_lshlrev_b32_e32 v4, 2, v9
	v_lshl_add_u64 v[28:29], v[10:11], 0, v[4:5]
	v_ashrrev_i32_e32 v10, 9, v8
	v_and_b32_e32 v10, 0xffffff00, v10
	v_ashrrev_i32_e32 v11, 31, v10
	v_lshl_add_u64 v[10:11], v[10:11], 2, s[8:9]
	v_lshl_add_u64 v[14:15], v[10:11], 0, v[4:5]
	global_load_dwordx4 v[10:13], v[14:15], off offset:16
	s_nop 0
	global_load_dwordx4 v[14:17], v[14:15], off
	s_nop 0
	global_load_dwordx4 v[18:21], v[28:29], off offset:16
	global_load_dwordx4 v[22:25], v[28:29], off
	s_mov_b64 s[24:25], 0x1000
	v_lshl_add_u64 v[30:31], v[28:29], 0, s[24:25]
	global_load_dwordx4 v[168:171], v[28:29], off offset:1040
	global_load_dwordx4 v[172:175], v[28:29], off offset:1024
	global_load_dwordx4 v[176:179], v[28:29], off offset:2064
	global_load_dwordx4 v[180:183], v[28:29], off offset:2048
	global_load_dwordx4 v[184:187], v[28:29], off offset:3088
	global_load_dwordx4 v[188:191], v[28:29], off offset:3072
	global_load_dwordx4 v[192:195], v[30:31], off
	global_load_dwordx4 v[196:199], v[30:31], off offset:16
	global_load_dwordx4 v[200:203], v[30:31], off offset:1024
	global_load_dwordx4 v[204:207], v[30:31], off offset:1040
	global_load_dwordx4 v[208:211], v[30:31], off offset:2048
	global_load_dwordx4 v[212:215], v[30:31], off offset:2064
	v_add_u32_e32 v8, s12, v8
	v_add_u32_e32 v6, s13, v6
	s_waitcnt vmcnt(12)
	v_pk_add_f32 v[20:21], v[12:13], v[20:21]
	v_pk_add_f32 v[24:25], v[16:17], v[24:25]
	v_pk_add_f32 v[22:23], v[14:15], v[22:23]
	v_pk_add_f32 v[18:19], v[10:11], v[18:19]
	global_load_dwordx4 v[10:13], v[30:31], off offset:3072
	s_nop 0
	global_load_dwordx4 v[14:17], v[30:31], off offset:3088
	s_waitcnt vmcnt(12)
	v_pk_add_f32 v[20:21], v[20:21], v[170:171]
	v_pk_add_f32 v[24:25], v[24:25], v[174:175]
	v_pk_add_f32 v[22:23], v[22:23], v[172:173]
	v_pk_add_f32 v[18:19], v[18:19], v[168:169]
	s_waitcnt vmcnt(10)
	v_pk_add_f32 v[20:21], v[20:21], v[178:179]
	v_pk_add_f32 v[24:25], v[24:25], v[182:183]
	v_pk_add_f32 v[22:23], v[22:23], v[180:181]
	v_pk_add_f32 v[18:19], v[18:19], v[176:177]
	s_waitcnt vmcnt(8)
	v_pk_add_f32 v[20:21], v[20:21], v[186:187]
	v_pk_add_f32 v[24:25], v[24:25], v[190:191]
	v_pk_add_f32 v[22:23], v[22:23], v[188:189]
	v_pk_add_f32 v[18:19], v[18:19], v[184:185]
	s_waitcnt vmcnt(6)
	v_pk_add_f32 v[20:21], v[20:21], v[198:199]
	v_pk_add_f32 v[24:25], v[24:25], v[194:195]
	v_pk_add_f32 v[22:23], v[22:23], v[192:193]
	v_pk_add_f32 v[18:19], v[18:19], v[196:197]
	s_waitcnt vmcnt(4)
	v_pk_add_f32 v[20:21], v[20:21], v[206:207]
	v_pk_add_f32 v[24:25], v[24:25], v[202:203]
	v_pk_add_f32 v[22:23], v[22:23], v[200:201]
	v_pk_add_f32 v[18:19], v[18:19], v[204:205]
	s_waitcnt vmcnt(2)
	v_pk_add_f32 v[20:21], v[20:21], v[214:215]
	v_pk_add_f32 v[24:25], v[24:25], v[210:211]
	v_pk_add_f32 v[22:23], v[22:23], v[208:209]
	v_pk_add_f32 v[18:19], v[18:19], v[212:213]
	s_mov_b32 s24, 0x3ffff
	v_cmp_lt_i32_e32 vcc, s24, v8
	s_or_b64 s[10:11], vcc, s[10:11]
	s_waitcnt vmcnt(0)
	v_pk_add_f32 v[10:11], v[22:23], v[10:11]
	s_nop 0
	v_mul_f32_e32 v4, v10, v10
	v_fmamk_f32 v4, v4, 0xbdd2d3e8, v7
	v_mul_f32_e32 v4, v10, v4
	v_exp_f32_e32 v4, v4
	v_pk_add_f32 v[14:15], v[18:19], v[14:15]
	v_pk_add_f32 v[12:13], v[24:25], v[12:13]
	v_pk_add_f32 v[16:17], v[20:21], v[16:17]
	v_add_f32_e32 v4, 1.0, v4
	v_rcp_f32_e32 v18, v4
	v_mul_f32_e32 v4, v11, v11
	v_fmamk_f32 v4, v4, 0xbdd2d3e8, v7
	v_mul_f32_e32 v4, v11, v4
	v_exp_f32_e32 v4, v4
	v_mov_b32_e32 v23, v12
	v_mov_b32_e32 v22, v10
	v_add_f32_e32 v4, 1.0, v4
	v_rcp_f32_e32 v20, v4
	v_mul_f32_e32 v4, v12, v12
	v_fmamk_f32 v4, v4, 0xbdd2d3e8, v7
	v_mul_f32_e32 v4, v12, v4
	v_exp_f32_e32 v4, v4
	v_mov_b32_e32 v12, v11
	v_add_f32_e32 v4, 1.0, v4
	v_rcp_f32_e32 v19, v4
	v_mul_f32_e32 v4, v13, v13
	v_fmamk_f32 v4, v4, 0xbdd2d3e8, v7
	v_mul_f32_e32 v4, v13, v4
	v_exp_f32_e32 v4, v4
	v_pk_mul_f32 v[18:19], v[22:23], v[18:19]
	v_mov_b32_e32 v23, v16
	v_mov_b32_e32 v22, v14
	v_add_f32_e32 v4, 1.0, v4
	v_rcp_f32_e32 v21, v4
	v_mul_f32_e32 v4, v14, v14
	v_fmamk_f32 v4, v4, 0xbdd2d3e8, v7
	v_mul_f32_e32 v4, v14, v4
	v_exp_f32_e32 v4, v4
	v_pk_mul_f32 v[10:11], v[12:13], v[20:21]
	v_add_f32_e32 v4, 1.0, v4
	v_rcp_f32_e32 v12, v4
	v_mul_f32_e32 v4, v15, v15
	v_fmamk_f32 v4, v4, 0xbdd2d3e8, v7
	v_mul_f32_e32 v4, v15, v4
	v_exp_f32_e32 v4, v4
	s_nop 0
	v_add_f32_e32 v4, 1.0, v4
	v_rcp_f32_e32 v20, v4
	v_mul_f32_e32 v4, v16, v16
	v_fmamk_f32 v4, v4, 0xbdd2d3e8, v7
	v_mul_f32_e32 v4, v16, v4
	v_exp_f32_e32 v4, v4
	v_mov_b32_e32 v16, v15
	v_add_f32_e32 v4, 1.0, v4
	v_rcp_f32_e32 v13, v4
	v_mul_f32_e32 v4, v17, v17
	v_fmamk_f32 v4, v4, 0xbdd2d3e8, v7
	v_mul_f32_e32 v4, v17, v4
	v_exp_f32_e32 v4, v4
	v_pk_mul_f32 v[12:13], v[22:23], v[12:13]
	v_add_f32_e32 v4, 1.0, v4
	v_rcp_f32_e32 v21, v4
	v_bfe_u32 v4, v11, 16, 1
	v_add3_u32 v4, v11, v4, s14
	s_nop 0
	v_pk_mul_f32 v[14:15], v[16:17], v[20:21]
	s_nop 7
	v_bfe_u32 v16, v19, 16, 1
	s_nop 1
	v_add3_u32 v16, v19, v16, s14
	s_nop 3
	v_lshrrev_b32_e32 v11, 16, v16
	v_cvt_pk_bf16_f32 v13, v13, v15
	v_cvt_pk_bf16_f32 v12, v12, v14
	v_lshlrev_b64 v[14:15], 9, v[26:27]
	v_and_or_b32 v11, v4, s15, v11
	v_lshl_add_u64 v[14:15], s[6:7], 0, v[14:15]
	v_lshlrev_b32_e32 v4, 1, v9
	v_cvt_pk_bf16_f32 v10, v18, v10
	v_lshl_add_u64 v[14:15], v[14:15], 0, v[4:5]
	global_store_dwordx4 v[14:15], v[10:13], off
	s_andn2_b64 exec, exec, s[10:11]
	s_cbranch_execnz .LBB0_2023
